# baseline (speedup 1.0000x reference)
; __device__ __forceinline__ unsigned cvtpk(float lo, float hi) { f32x2_t v = {lo, hi}; bf16x2_t r = __builtin_convertvector(v, bf16x2_t); return *reinterpret_cast<unsigned*>(&r); }
; #define MFMA(a, b, c) __builtin_amdgcn_mfma_f32_16x16x32_bf16((a), (b), (c), 0, 0, 0)
; __device__ __forceinline__ void phase_dif_attn(const Params& p, char* lds) {
;     ...
;         float rsum = 0.f;
; #pragma unroll
;         for (int n = 0; n < 4; ++n)
; #pragma unroll
;           for (int j = 0; j < 4; ++j) { float pv = __builtin_amdgcn_exp2f(st[mi][n][j] - mnew); st[mi][n][j] = pv; rsum += pv; }
;         lrun[mi] = lrun[mi] * alpha + rsum;
; #pragma unroll
;         for (int ks = 0; ks < 2; ++ks) {
;           u32x4 v = {cvtpk(st[mi][2 * ks][0], st[mi][2 * ks][1]), cvtpk(st[mi][2 * ks][2], st[mi][2 * ks][3]),
;                      cvtpk(st[mi][2 * ks + 1][0], st[mi][2 * ks + 1][1]), cvtpk(st[mi][2 * ks + 1][2], st[mi][2 * ks + 1][3])};
;           pb[mi][ks] = *reinterpret_cast<bf16x8*>(&v);
;         }
;       }
; #pragma unroll
;       for (int dv = 0; dv < 8; ++dv)
; #pragma unroll
;         for (int ks = 0; ks < 2; ++ks) {
;           const char* vp = vbuf + (dv * 16 + l15) * 144 + (ks * 32 + quad * 4) * 2;
;           bf16x4 lo = *(const bf16x4*)vp, hi = *(const bf16x4*)(vp + 32);
;           bf16x8 va = {lo[0], lo[1], lo[2], lo[3], hi[0], hi[1], hi[2], hi[3]};
; #pragma unroll
;           for (int mi = 0; mi < 2; ++mi) oacc[mi][dv] = MFMA(va, pb[mi][ks], oacc[mi][dv]);
;           if (ks == 1 && (dv & 1)) __builtin_amdgcn_sched_barrier(0);
;         }
.Lattn_back1:
	v_exp_f32_e32 v120, v120
	v_exp_f32_e32 v104, v104
	v_exp_f32_e32 v121, v121
	v_exp_f32_e32 v105, v105
	v_exp_f32_e32 v122, v122
	v_exp_f32_e32 v106, v106
	v_exp_f32_e32 v123, v123
	v_exp_f32_e32 v107, v107
	v_exp_f32_e32 v116, v116
	v_exp_f32_e32 v100, v100
	v_exp_f32_e32 v117, v117
	v_exp_f32_e32 v101, v101
	v_exp_f32_e32 v118, v118
	v_exp_f32_e32 v102, v102
	v_exp_f32_e32 v119, v119
	v_exp_f32_e32 v103, v103
	v_cvt_pk_bf16_f32 v166, v120, v121
	v_cvt_pk_bf16_f32 v167, v122, v123
	v_cvt_pk_bf16_f32 v168, v116, v117
	v_cvt_pk_bf16_f32 v169, v118, v119
	v_cvt_pk_bf16_f32 v170, v104, v105
	v_cvt_pk_bf16_f32 v171, v106, v107
	v_cvt_pk_bf16_f32 v172, v100, v101
	v_cvt_pk_bf16_f32 v173, v102, v103
	v_pk_add_f32 v[120:121], v[120:121], v[122:123]
	v_pk_add_f32 v[104:105], v[104:105], v[106:107]
	v_pk_add_f32 v[116:117], v[116:117], v[118:119]
	v_pk_add_f32 v[100:101], v[100:101], v[102:103]
	v_pk_add_f32 v[120:121], v[120:121], v[116:117]
	v_pk_add_f32 v[104:105], v[104:105], v[100:101]
	v_exp_f32_e32 v112, v112
	v_exp_f32_e32 v96, v96
	s_waitcnt lgkmcnt(12)
	v_mfma_f32_16x16x32_bf16 v[60:63], v[178:181], v[166:169], v[60:63]
	v_exp_f32_e32 v113, v113
	v_exp_f32_e32 v97, v97
	v_exp_f32_e32 v114, v114
	v_mfma_f32_16x16x32_bf16 v[56:59], v[178:181], v[170:173], v[56:59]
	v_exp_f32_e32 v98, v98
	v_exp_f32_e32 v115, v115
	ds_read_b64 v[236:237], v198 offset:24320
	ds_read_b64 v[238:239], v198 offset:24352
	s_waitcnt lgkmcnt(12)
	v_mfma_f32_16x16x32_bf16 v[48:51], v[182:185], v[166:169], v[48:51]
	v_exp_f32_e32 v99, v99
	v_exp_f32_e32 v108, v108
	v_exp_f32_e32 v92, v92
	v_mfma_f32_16x16x32_bf16 v[52:55], v[182:185], v[170:173], v[52:55]
	v_exp_f32_e32 v109, v109
	v_exp_f32_e32 v93, v93
	ds_read_b64 v[178:179], v198 offset:8256
	ds_read_b64 v[180:181], v198 offset:8288
	s_waitcnt lgkmcnt(12)
	v_mfma_f32_16x16x32_bf16 v[44:47], v[186:189], v[166:169], v[44:47]
	v_exp_f32_e32 v110, v110
	v_exp_f32_e32 v94, v94
	v_exp_f32_e32 v111, v111
	v_mfma_f32_16x16x32_bf16 v[40:43], v[186:189], v[170:173], v[40:43]
	v_exp_f32_e32 v95, v95
	v_cvt_pk_bf16_f32 v174, v112, v113
	ds_read_b64 v[182:183], v198 offset:10560
	ds_read_b64 v[184:185], v198 offset:10592
	s_waitcnt lgkmcnt(12)
	v_mfma_f32_16x16x32_bf16 v[36:39], v[190:193], v[166:169], v[36:39]
	v_cvt_pk_bf16_f32 v175, v114, v115
	v_cvt_pk_bf16_f32 v176, v108, v109
	v_cvt_pk_bf16_f32 v177, v110, v111
	v_mfma_f32_16x16x32_bf16 v[32:35], v[190:193], v[170:173], v[32:35]
	v_cvt_pk_bf16_f32 v248, v96, v97
	v_cvt_pk_bf16_f32 v249, v98, v99
	ds_read_b64 v[186:187], v198 offset:12864
	ds_read_b64 v[188:189], v198 offset:12896
	s_waitcnt lgkmcnt(12)
	v_mfma_f32_16x16x32_bf16 v[28:31], v[194:197], v[166:169], v[28:31]
	v_cvt_pk_bf16_f32 v250, v92, v93
	v_cvt_pk_bf16_f32 v251, v94, v95
	v_pk_add_f32 v[112:113], v[112:113], v[114:115]
	v_mfma_f32_16x16x32_bf16 v[24:27], v[194:197], v[170:173], v[24:27]
	v_pk_add_f32 v[96:97], v[96:97], v[98:99]
	v_pk_add_f32 v[108:109], v[108:109], v[110:111]
	ds_read_b64 v[190:191], v198 offset:15168
	ds_read_b64 v[192:193], v198 offset:15200
	s_waitcnt lgkmcnt(12)
	v_mfma_f32_16x16x32_bf16 v[20:23], v[228:231], v[166:169], v[20:23]
	v_pk_add_f32 v[92:93], v[92:93], v[94:95]
	v_pk_add_f32 v[112:113], v[112:113], v[108:109]
	v_pk_add_f32 v[96:97], v[96:97], v[92:93]
	v_mfma_f32_16x16x32_bf16 v[16:19], v[228:231], v[170:173], v[16:19]
	v_pk_add_f32 v[120:121], v[120:121], v[112:113]
	v_pk_add_f32 v[104:105], v[104:105], v[96:97]
	ds_read_b64 v[194:195], v198 offset:17472
	ds_read_b64 v[196:197], v198 offset:17504
	s_waitcnt lgkmcnt(12)
	v_mfma_f32_16x16x32_bf16 v[12:15], v[232:235], v[166:169], v[12:15]
	v_add_f32_e32 v120, v120, v121
	v_add_f32_e32 v104, v104, v105
	v_add_f32_e32 v165, v165, v120
	v_mfma_f32_16x16x32_bf16 v[8:11], v[232:235], v[170:173], v[8:11]
	v_add_f32_e32 v164, v164, v104
	ds_read_b64 v[228:229], v198 offset:19776
	ds_read_b64 v[230:231], v198 offset:19808
	s_waitcnt lgkmcnt(12)
	v_mfma_f32_16x16x32_bf16 v[4:7], v[236:239], v[166:169], v[4:7]
	v_mfma_f32_16x16x32_bf16 v[0:3], v[236:239], v[170:173], v[0:3]
	ds_read_b64 v[232:233], v198 offset:22080
	ds_read_b64 v[234:235], v198 offset:22112
	s_add_i32 s6, s6, 1
	s_waitcnt lgkmcnt(12)
	v_mfma_f32_16x16x32_bf16 v[60:63], v[178:181], v[174:177], v[60:63]
	v_mfma_f32_16x16x32_bf16 v[56:59], v[178:181], v[248:251], v[56:59]
	ds_read_b64 v[236:237], v198 offset:24384
	ds_read_b64 v[238:239], v198 offset:24416
	s_waitcnt lgkmcnt(12)
	v_mfma_f32_16x16x32_bf16 v[48:51], v[182:185], v[174:177], v[48:51]
	v_mfma_f32_16x16x32_bf16 v[52:55], v[182:185], v[248:251], v[52:55]
	s_waitcnt lgkmcnt(10)
	v_mfma_f32_16x16x32_bf16 v[44:47], v[186:189], v[174:177], v[44:47]
	v_mfma_f32_16x16x32_bf16 v[40:43], v[186:189], v[248:251], v[40:43]
	s_bitcmp1_b32 s6, 0
	s_cselect_b32 s8, 0x6800, 0
	s_add_i32 s8, s8, 0
	v_add_u32_e32 v92, s8, v149
	v_add3_u32 v92, v92, v151, v152
	s_waitcnt vmcnt(2)
	ds_write_b128 v92, v[80:83]
	v_add3_u32 v80, s8, v153, v154
	s_add_i32 s7, s7, 64
	s_waitcnt vmcnt(1)
	ds_write_b128 v80, v[84:87] offset:8192
	v_add3_u32 v80, s8, v155, v154
	s_waitcnt vmcnt(0)
	ds_write_b128 v80, v[88:91] offset:8192
	s_waitcnt lgkmcnt(11)
	v_mfma_f32_16x16x32_bf16 v[36:39], v[190:193], v[174:177], v[36:39]
	v_mfma_f32_16x16x32_bf16 v[32:35], v[190:193], v[248:251], v[32:35]
	s_waitcnt lgkmcnt(9)
	v_mfma_f32_16x16x32_bf16 v[28:31], v[194:197], v[174:177], v[28:31]
	v_mfma_f32_16x16x32_bf16 v[24:27], v[194:197], v[248:251], v[24:27]
	s_waitcnt lgkmcnt(7)
	v_mfma_f32_16x16x32_bf16 v[20:23], v[228:231], v[174:177], v[20:23]
	v_mfma_f32_16x16x32_bf16 v[16:19], v[228:231], v[248:251], v[16:19]
	s_waitcnt lgkmcnt(5)
	v_mfma_f32_16x16x32_bf16 v[12:15], v[232:235], v[174:177], v[12:15]
	v_mfma_f32_16x16x32_bf16 v[8:11], v[232:235], v[248:251], v[8:11]
	s_waitcnt lgkmcnt(3)
	v_mfma_f32_16x16x32_bf16 v[4:7], v[236:239], v[174:177], v[4:7]
	v_mfma_f32_16x16x32_bf16 v[0:3], v[236:239], v[248:251], v[0:3]
	v_mov_b32_e32 v116, v165
	v_mov_b32_e32 v101, v164
	s_cmp_eq_u32 s5, s6
	s_waitcnt lgkmcnt(0)
	s_barrier
	s_cbranch_scc1 .LBB0_508
	s_branch .LBB0_501
